# v36 + P4 weight conversion: the first item's gain loads no longer wait (vmcnt 0) before the second item's loads are issued; its scaling is done after both items' loads are in flight
# speedup vs baseline: 1.0023x; 1.0023x over previous
; #define LAS __attribute__((address_space(3)))
; DI void p0_load(const TItem& t, f32x4 (&v)[8], int lane) {
;     const int nblk = t.N / 32, kb = t.item / nblk, nb = t.item % nblk, k0 = 64 * kb, n0 = 32 * nb, c = lane & 7, rr = lane >> 3;
; #pragma unroll
;     for (int i = 0; i < 8; ++i) v[i] = __builtin_nontemporal_load((const f32x4*)(t.W + (size_t)(k0 + 8 * i + rr) * t.N + n0 + 4 * c));
;     if (t.rs) {
; #pragma unroll
;         for (int i = 0; i < 8; ++i) v[i] = v[i] * t.rs[k0 + 8 * i + rr];
;     }
; template <class Resolve>
; DI void p0_convert(const Resolve R, int first, int stride, int total, LAS float* scr, int lane) {
;     for (int it = first; it < total; it += 2 * stride) {
;         const bool two = it + stride < total;
;         const TItem t0 = R(it), t1 = R(two ? it + stride : it);
;         f32x4 v0[8], v1[8];
;         p0_load(t0, v0, lane);
;         if (two) p0_load(t1, v1, lane);
.LBB0_450:
	s_lshr_b32 s5, s13, 5
	v_cvt_f32_u32_e32 v32, s5
	s_sub_i32 s25, 0, s5
	s_abs_i32 s12, s10
	s_ashr_i32 s11, s10, 31
	v_rcp_iflag_f32_e32 v32, v32
	s_nop 0
	v_mul_f32_e32 v32, 0x4f7ffffe, v32
	v_cvt_u32_f32_e32 v32, v32
	s_nop 0
	v_readfirstlane_b32 s26, v32
	s_mul_i32 s25, s25, s26
	s_mul_hi_u32 s25, s26, s25
	s_add_i32 s26, s26, s25
	s_mul_hi_u32 s25, s12, s26
	s_mul_i32 s26, s25, s5
	s_sub_i32 s12, s12, s26
	s_add_i32 s27, s25, 1
	s_sub_i32 s26, s12, s5
	s_cmp_ge_u32 s12, s5
	s_cselect_b32 s25, s27, s25
	s_cselect_b32 s12, s26, s12
	s_add_i32 s26, s25, 1
	s_cmp_ge_u32 s12, s5
	s_cselect_b32 s12, s26, s25
	s_xor_b32 s12, s12, s11
	s_sub_i32 s11, s12, s11
	s_mul_i32 s5, s11, s5
	s_lshl_b32 s12, s11, 6
	s_sub_i32 s5, s10, s5
	v_or_b32_e32 v70, s12, v72
	s_lshl_b32 s10, s5, 5
	v_or_b32_e32 v34, 8, v70
	v_or_b32_e32 v40, 16, v70
	v_or_b32_e32 v42, 24, v70
	v_or_b32_e32 v48, 32, v70
	v_or_b32_e32 v50, 40, v70
	v_or_b32_e32 v56, 48, v70
	v_or_b32_e32 v58, 56, v70
	v_mad_i64_i32 v[32:33], s[26:27], v70, s13, 0
	s_ashr_i32 s11, s10, 31
	v_mad_i64_i32 v[34:35], s[28:29], v34, s13, 0
	v_mad_i64_i32 v[40:41], s[28:29], v40, s13, 0
	v_mad_i64_i32 v[42:43], s[28:29], v42, s13, 0
	v_mad_i64_i32 v[48:49], s[28:29], v48, s13, 0
	v_mad_i64_i32 v[50:51], s[28:29], v50, s13, 0
	v_mad_i64_i32 v[56:57], s[28:29], v56, s13, 0
	v_mad_i64_i32 v[58:59], s[28:29], v58, s13, 0
	v_lshl_add_u64 v[32:33], v[32:33], 2, s[18:19]
	s_lshl_b64 s[26:27], s[10:11], 2
	v_lshl_add_u64 v[34:35], v[34:35], 2, s[18:19]
	v_lshl_add_u64 v[40:41], v[40:41], 2, s[18:19]
	v_lshl_add_u64 v[42:43], v[42:43], 2, s[18:19]
	v_lshl_add_u64 v[48:49], v[48:49], 2, s[18:19]
	v_lshl_add_u64 v[50:51], v[50:51], 2, s[18:19]
	v_lshl_add_u64 v[56:57], v[56:57], 2, s[18:19]
	v_lshl_add_u64 v[58:59], v[58:59], 2, s[18:19]
	v_lshl_add_u64 v[32:33], v[32:33], 0, s[26:27]
	v_lshl_add_u64 v[34:35], v[34:35], 0, s[26:27]
	v_lshl_add_u64 v[40:41], v[40:41], 0, s[26:27]
	v_lshl_add_u64 v[42:43], v[42:43], 0, s[26:27]
	v_lshl_add_u64 v[48:49], v[48:49], 0, s[26:27]
	v_lshl_add_u64 v[50:51], v[50:51], 0, s[26:27]
	v_lshl_add_u64 v[56:57], v[56:57], 0, s[26:27]
	v_lshl_add_u64 v[58:59], v[58:59], 0, s[26:27]
	v_lshl_add_u64 v[32:33], v[32:33], 0, v[68:69]
	v_lshl_add_u64 v[34:35], v[34:35], 0, v[68:69]
	v_lshl_add_u64 v[40:41], v[40:41], 0, v[68:69]
	v_lshl_add_u64 v[42:43], v[42:43], 0, v[68:69]
	v_lshl_add_u64 v[48:49], v[48:49], 0, v[68:69]
	v_lshl_add_u64 v[50:51], v[50:51], 0, v[68:69]
	v_lshl_add_u64 v[56:57], v[56:57], 0, v[68:69]
	v_lshl_add_u64 v[58:59], v[58:59], 0, v[68:69]
	global_load_dwordx4 v[36:39], v[32:33], off nt
	s_nop 0
	global_load_dwordx4 v[32:35], v[34:35], off nt
	s_nop 0
	global_load_dwordx4 v[44:47], v[40:41], off nt
	s_nop 0
	global_load_dwordx4 v[40:43], v[42:43], off nt
	s_nop 0
	global_load_dwordx4 v[52:55], v[48:49], off nt
	s_nop 0
	global_load_dwordx4 v[48:51], v[50:51], off nt
	s_nop 0
	global_load_dwordx4 v[60:63], v[56:57], off nt
	s_nop 0
	global_load_dwordx4 v[56:59], v[58:59], off nt
	s_cmp_eq_u64 s[0:1], 0
	s_cselect_b32 s32, 0, 1
	s_cbranch_scc1 .LBB0_452
	v_ashrrev_i32_e32 v71, 31, v70
	v_lshl_add_u64 v[70:71], v[70:71], 2, s[0:1]
	global_load_dword v92, v[70:71], off
	global_load_dword v94, v[70:71], off offset:32
	global_load_dword v96, v[70:71], off offset:64
	global_load_dword v98, v[70:71], off offset:96
	global_load_dword v100, v[70:71], off offset:128
	global_load_dword v102, v[70:71], off offset:160
	global_load_dword v104, v[70:71], off offset:192
	global_load_dword v106, v[70:71], off offset:224

; #define LAS __attribute__((address_space(3)))
; DI unsigned pk2(float lo, float hi) { f32x2 v = {lo, hi}; return __builtin_bit_cast(unsigned, __builtin_convertvector(v, bf16x2v)); }
; DI void p0_store(const TItem& t, const f32x4 (&v)[8], LAS float* scr, int lane) {
;     const int nblk = t.N / 32, kb = t.item / nblk, nb = t.item % nblk, k0 = 64 * kb, n0 = 32 * nb, c = lane & 7, rr = lane >> 3;
; #pragma unroll
;     for (int i = 0; i < 8; ++i) { LAS float* d = scr + (8 * i + rr) * 33 + 4 * c; d[0] = v[i][0]; d[1] = v[i][1]; d[2] = v[i][2]; d[3] = v[i][3]; }
;     asm volatile("s_waitcnt lgkmcnt(0)" ::: "memory");
; #pragma unroll
;     for (int j = 0; j < 4; ++j) { const int n = (lane >> 3) + 8 * j; const LAS float* s = scr + (8 * c) * 33 + n;
;         u32x4 o; o.x = pk2(s[0 * 33], s[1 * 33]); o.y = pk2(s[2 * 33], s[3 * 33]); o.z = pk2(s[4 * 33], s[5 * 33]); o.w = pk2(s[6 * 33], s[7 * 33]);
;         *(u32x4*)(t.WT + (size_t)(n0 + n) * t.K + k0 + 8 * c) = o; }
;     asm volatile("s_waitcnt lgkmcnt(0)" ::: "memory");
; }
; template <class Resolve>
; DI void p0_convert(const Resolve R, int first, int stride, int total, LAS float* scr, int lane) {
;     ...
;         p0_load(t0, v0, lane);
;         if (two) p0_load(t1, v1, lane);
;         p0_store(t0, v0, scr, lane);
.LBB0_455:
	s_waitcnt vmcnt(0)
	s_cmp_eq_u32 s32, 0
	s_cbranch_scc1 .Lmy_g0skip
	v_pk_mul_f32 v[38:39], v[38:39], v[92:93] op_sel_hi:[1,0]
	v_pk_mul_f32 v[36:37], v[36:37], v[92:93] op_sel_hi:[1,0]
	v_pk_mul_f32 v[34:35], v[34:35], v[94:95] op_sel_hi:[1,0]
	v_pk_mul_f32 v[32:33], v[32:33], v[94:95] op_sel_hi:[1,0]
	v_pk_mul_f32 v[46:47], v[46:47], v[96:97] op_sel_hi:[1,0]
	v_pk_mul_f32 v[44:45], v[44:45], v[96:97] op_sel_hi:[1,0]
	v_pk_mul_f32 v[42:43], v[42:43], v[98:99] op_sel_hi:[1,0]
	v_pk_mul_f32 v[40:41], v[40:41], v[98:99] op_sel_hi:[1,0]
	v_pk_mul_f32 v[54:55], v[54:55], v[100:101] op_sel_hi:[1,0]
	v_pk_mul_f32 v[52:53], v[52:53], v[100:101] op_sel_hi:[1,0]
	v_pk_mul_f32 v[50:51], v[50:51], v[102:103] op_sel_hi:[1,0]
	v_pk_mul_f32 v[48:49], v[48:49], v[102:103] op_sel_hi:[1,0]
	v_pk_mul_f32 v[62:63], v[62:63], v[104:105] op_sel_hi:[1,0]
	v_pk_mul_f32 v[60:61], v[60:61], v[104:105] op_sel_hi:[1,0]
	v_pk_mul_f32 v[58:59], v[58:59], v[106:107] op_sel_hi:[1,0]
	v_pk_mul_f32 v[56:57], v[56:57], v[106:107] op_sel_hi:[1,0]
.Lmy_g0skip:
	ds_write2_b32 v77, v36, v37 offset1:1
	ds_write2_b32 v77, v38, v39 offset0:2 offset1:3
	v_add_u32_e32 v36, 0x420, v77
	ds_write2_b32 v36, v32, v33 offset1:1
	v_add_u32_e32 v32, 0x428, v77
	ds_write2_b32 v32, v34, v35 offset1:1
	v_add_u32_e32 v32, 0x840, v77
	ds_write2_b32 v32, v44, v45 offset1:1
	v_add_u32_e32 v32, 0x848, v77
	ds_write2_b32 v32, v46, v47 offset1:1
	v_add_u32_e32 v32, 0xc60, v77
	ds_write2_b32 v32, v40, v41 offset1:1
	v_add_u32_e32 v32, 0xc68, v77
	ds_write2_b32 v32, v42, v43 offset1:1
	v_add_u32_e32 v32, 0x1080, v77
	ds_write2_b32 v32, v52, v53 offset1:1
	v_add_u32_e32 v32, 0x1088, v77
	ds_write2_b32 v32, v54, v55 offset1:1
	v_add_u32_e32 v32, 0x14a0, v77
	ds_write2_b32 v32, v48, v49 offset1:1
	v_add_u32_e32 v32, 0x14a8, v77
	ds_write2_b32 v32, v50, v51 offset1:1
	v_add_u32_e32 v32, 0x18c0, v77
	ds_write2_b32 v32, v60, v61 offset1:1
	v_add_u32_e32 v32, 0x18c8, v77
	ds_write2_b32 v32, v62, v63 offset1:1
	v_add_u32_e32 v32, 0x1ce0, v77
	ds_write2_b32 v32, v56, v57 offset1:1
	v_add_u32_e32 v32, 0x1ce8, v77
	ds_write2_b32 v32, v58, v59 offset1:1
	s_waitcnt lgkmcnt(0)
	ds_read2_b32 v[36:37], v76 offset0:33 offset1:41
	ds_read2_b32 v[38:39], v76 offset1:8
	ds_read2_b32 v[40:41], v76 offset0:66 offset1:74
	ds_read2_b32 v[42:43], v76 offset0:99 offset1:107
	ds_read2_b32 v[44:45], v76 offset0:132 offset1:140
	ds_read2_b32 v[46:47], v76 offset0:165 offset1:173
	ds_read2_b32 v[48:49], v76 offset0:198 offset1:206
	ds_read2_b32 v[50:51], v76 offset0:231 offset1:239
	v_or_b32_e32 v52, s10, v72
	v_ashrrev_i32_e32 v53, 31, v52
	s_ashr_i32 s13, s12, 31
	v_lshlrev_b64 v[52:53], 12, v[52:53]
	v_lshl_add_u64 v[52:53], s[8:9], 0, v[52:53]
	s_lshl_b64 s[2:3], s[12:13], 1
	v_lshl_add_u64 v[52:53], v[52:53], 0, s[2:3]
	s_waitcnt lgkmcnt(6)
	v_cvt_pk_bf16_f32 v32, v38, v36
	s_waitcnt lgkmcnt(4)
	v_cvt_pk_bf16_f32 v33, v40, v42
	s_waitcnt lgkmcnt(2)
	v_cvt_pk_bf16_f32 v34, v44, v46
	s_waitcnt lgkmcnt(0)
	v_cvt_pk_bf16_f32 v35, v48, v50
	v_lshl_add_u64 v[52:53], v[52:53], 0, v[64:65]
	v_or_b32_e32 v36, s10, v73
	global_store_dwordx4 v[52:53], v[32:35], off
	s_and_b64 vcc, exec, s[0:1]
	s_nop 0
	v_cvt_pk_bf16_f32 v32, v39, v37
	v_ashrrev_i32_e32 v37, 31, v36
	v_lshlrev_b64 v[36:37], 12, v[36:37]
	v_lshl_add_u64 v[36:37], s[8:9], 0, v[36:37]
	v_lshl_add_u64 v[36:37], v[36:37], 0, s[2:3]
	v_cvt_pk_bf16_f32 v33, v41, v43
	v_cvt_pk_bf16_f32 v34, v45, v47
	v_cvt_pk_bf16_f32 v35, v49, v51
	v_lshl_add_u64 v[36:37], v[36:37], 0, v[64:65]
	ds_read2_b32 v[38:39], v76 offset0:49 offset1:57
	ds_read2_b32 v[40:41], v76 offset0:16 offset1:24
	ds_read2_b32 v[42:43], v76 offset0:82 offset1:90
	ds_read2_b32 v[44:45], v76 offset0:115 offset1:123
	ds_read2_b32 v[46:47], v76 offset0:148 offset1:156
	ds_read2_b32 v[48:49], v76 offset0:181 offset1:189
	ds_read2_b32 v[50:51], v76 offset0:214 offset1:222
	ds_read2_b32 v[52:53], v76 offset0:247 offset1:255
	global_store_dwordx4 v[36:37], v[32:35], off
	v_or_b32_e32 v36, s10, v74
	v_ashrrev_i32_e32 v37, 31, v36
	v_lshlrev_b64 v[36:37], 12, v[36:37]
	v_lshl_add_u64 v[36:37], s[8:9], 0, v[36:37]
	v_lshl_add_u64 v[36:37], v[36:37], 0, s[2:3]
	s_waitcnt lgkmcnt(6)
	v_cvt_pk_bf16_f32 v32, v40, v38
	s_waitcnt lgkmcnt(4)
	v_cvt_pk_bf16_f32 v33, v42, v44
	s_waitcnt lgkmcnt(2)
	v_cvt_pk_bf16_f32 v34, v46, v48
	s_waitcnt lgkmcnt(0)
	v_cvt_pk_bf16_f32 v35, v50, v52
	v_lshl_add_u64 v[36:37], v[36:37], 0, v[64:65]
	global_store_dwordx4 v[36:37], v[32:35], off
	v_or_b32_e32 v36, s10, v75
	v_ashrrev_i32_e32 v37, 31, v36
	v_lshlrev_b64 v[36:37], 12, v[36:37]
	v_lshl_add_u64 v[36:37], s[8:9], 0, v[36:37]
	v_lshl_add_u64 v[36:37], v[36:37], 0, s[2:3]
	v_cvt_pk_bf16_f32 v32, v41, v39
	v_cvt_pk_bf16_f32 v33, v43, v45
	v_cvt_pk_bf16_f32 v34, v47, v49
	v_cvt_pk_bf16_f32 v35, v51, v53
	v_lshl_add_u64 v[36:37], v[36:37], 0, v[64:65]
	global_store_dwordx4 v[36:37], v[32:35], off
	s_waitcnt lgkmcnt(0)
	s_cbranch_vccnz .LBB0_439
; #define LAS __attribute__((address_space(3)))
; DI unsigned pk2(float lo, float hi) { f32x2 v = {lo, hi}; return __builtin_bit_cast(unsigned, __builtin_convertvector(v, bf16x2v)); }
; DI void p0_store(const TItem& t, const f32x4 (&v)[8], LAS float* scr, int lane) {
;     const int nblk = t.N / 32, kb = t.item / nblk, nb = t.item % nblk, k0 = 64 * kb, n0 = 32 * nb, c = lane & 7, rr = lane >> 3;
; #pragma unroll
;     for (int i = 0; i < 8; ++i) { LAS float* d = scr + (8 * i + rr) * 33 + 4 * c; d[0] = v[i][0]; d[1] = v[i][1]; d[2] = v[i][2]; d[3] = v[i][3]; }
;     asm volatile("s_waitcnt lgkmcnt(0)" ::: "memory");
; #pragma unroll
;     for (int j = 0; j < 4; ++j) { const int n = (lane >> 3) + 8 * j; const LAS float* s = scr + (8 * c) * 33 + n;
;         u32x4 o; o.x = pk2(s[0 * 33], s[1 * 33]); o.y = pk2(s[2 * 33], s[3 * 33]); o.z = pk2(s[4 * 33], s[5 * 33]); o.w = pk2(s[6 * 33], s[7 * 33]);
;         *(u32x4*)(t.WT + (size_t)(n0 + n) * t.K + k0 + 8 * c) = o; }
;     asm volatile("s_waitcnt lgkmcnt(0)" ::: "memory");
; }
; template <class Resolve>
; DI void p0_convert(const Resolve R, int first, int stride, int total, LAS float* scr, int lane) {
;     ...
;         p0_store(t0, v0, scr, lane);
;         if (two) p0_store(t1, v1, scr + 64 * 33, lane);
	s_lshr_b32 s1, s24, 5
	v_cvt_f32_u32_e32 v32, s1
	s_sub_i32 s3, 0, s1
	v_add_u32_e32 v33, 0x2100, v77
	v_add_u32_e32 v34, 0x2108, v77
	v_rcp_iflag_f32_e32 v32, v32
	ds_write2_b32 v33, v0, v1 offset1:1
	ds_write2_b32 v34, v2, v3 offset1:1
	s_abs_i32 s2, s23
	s_ashr_i32 s0, s23, 31
	v_mul_f32_e32 v32, 0x4f7ffffe, v32
	v_cvt_u32_f32_e32 v32, v32
	v_add_u32_e32 v54, 0x2000, v76
	v_add_u32_e32 v55, 0x2400, v76
	v_readfirstlane_b32 s5, v32
	s_mul_i32 s3, s3, s5
	v_add_u32_e32 v32, 0x2520, v77
	s_mul_hi_u32 s3, s5, s3
	ds_write2_b32 v32, v4, v5 offset1:1
	v_add_u32_e32 v32, 0x2528, v77
	s_add_i32 s5, s5, s3
	ds_write2_b32 v32, v6, v7 offset1:1
	v_add_u32_e32 v32, 0x2940, v77
	s_mul_hi_u32 s3, s2, s5
	ds_write2_b32 v32, v8, v9 offset1:1
	v_add_u32_e32 v32, 0x2948, v77
	s_mul_i32 s5, s3, s1
	ds_write2_b32 v32, v10, v11 offset1:1
	v_add_u32_e32 v32, 0x2d60, v77
	s_sub_i32 s2, s2, s5
	ds_write2_b32 v32, v12, v13 offset1:1
	v_add_u32_e32 v32, 0x2d68, v77
	s_add_i32 s8, s3, 1
	s_sub_i32 s5, s2, s1
	ds_write2_b32 v32, v14, v15 offset1:1
	v_add_u32_e32 v32, 0x3180, v77
	s_cmp_ge_u32 s2, s1
	ds_write2_b32 v32, v16, v17 offset1:1
	v_add_u32_e32 v32, 0x3188, v77
	s_cselect_b32 s3, s8, s3
	ds_write2_b32 v32, v18, v19 offset1:1
	v_add_u32_e32 v32, 0x35a0, v77
	s_cselect_b32 s2, s5, s2
	s_add_i32 s5, s3, 1
	ds_write2_b32 v32, v20, v21 offset1:1
	v_add_u32_e32 v32, 0x35a8, v77
	s_cmp_ge_u32 s2, s1
	ds_write2_b32 v32, v22, v23 offset1:1
	v_add_u32_e32 v32, 0x39c0, v77
	s_cselect_b32 s2, s5, s3
	ds_write2_b32 v32, v24, v25 offset1:1
	v_add_u32_e32 v32, 0x39c8, v77
	s_xor_b32 s2, s2, s0
	ds_write2_b32 v32, v26, v27 offset1:1
	v_add_u32_e32 v32, 0x3de0, v77
	s_sub_i32 s2, s2, s0
	ds_write2_b32 v32, v28, v29 offset1:1
	v_add_u32_e32 v32, 0x3de8, v77
	s_lshl_b32 s0, s2, 6
	ds_write2_b32 v32, v30, v31 offset1:1
	s_mul_i32 s2, s2, s1
	s_sub_i32 s1, s23, s2
	s_waitcnt lgkmcnt(0)
	s_lshl_b32 s5, s1, 5
	ds_read2_b32 v[36:37], v54 offset0:97 offset1:105
	ds_read2_b32 v[38:39], v54 offset0:64 offset1:72
	ds_read2_b32 v[40:41], v54 offset0:130 offset1:138
	ds_read2_b32 v[42:43], v54 offset0:163 offset1:171
	ds_read2_b32 v[44:45], v54 offset0:196 offset1:204
	ds_read2_b32 v[46:47], v54 offset0:229 offset1:237
	ds_read2_b32 v[48:49], v55 offset0:6 offset1:14
	ds_read2_b32 v[50:51], v55 offset0:39 offset1:47
	s_waitcnt lgkmcnt(6)
	v_cvt_pk_bf16_f32 v32, v38, v36
	v_or_b32_e32 v36, s5, v72
	s_ashr_i32 s1, s0, 31
	v_mad_i64_i32 v[52:53], s[2:3], s4, v36, 0
	v_lshl_add_u64 v[52:53], v[52:53], 1, s[6:7]
	s_lshl_b64 s[0:1], s[0:1], 1
	v_lshl_add_u64 v[52:53], v[52:53], 0, s[0:1]
	s_waitcnt lgkmcnt(4)
	v_cvt_pk_bf16_f32 v33, v40, v42
	s_waitcnt lgkmcnt(2)
	v_cvt_pk_bf16_f32 v34, v44, v46
	s_waitcnt lgkmcnt(0)
	v_cvt_pk_bf16_f32 v35, v48, v50
	v_lshl_add_u64 v[52:53], v[52:53], 0, v[64:65]
	v_or_b32_e32 v36, s5, v73
	global_store_dwordx4 v[52:53], v[32:35], off
	s_nop 1
	v_cvt_pk_bf16_f32 v32, v39, v37
	v_mad_i64_i32 v[36:37], s[2:3], s4, v36, 0
	v_lshl_add_u64 v[36:37], v[36:37], 1, s[6:7]
	v_lshl_add_u64 v[36:37], v[36:37], 0, s[0:1]
	v_cvt_pk_bf16_f32 v33, v41, v43
	v_cvt_pk_bf16_f32 v34, v45, v47
	v_cvt_pk_bf16_f32 v35, v49, v51
	v_lshl_add_u64 v[36:37], v[36:37], 0, v[64:65]
	ds_read2_b32 v[38:39], v54 offset0:80 offset1:88
	ds_read2_b32 v[40:41], v54 offset0:113 offset1:121
	ds_read2_b32 v[42:43], v54 offset0:146 offset1:154
	ds_read2_b32 v[44:45], v54 offset0:179 offset1:187
	ds_read2_b32 v[46:47], v54 offset0:212 offset1:220
	ds_read2_b32 v[48:49], v54 offset0:245 offset1:253
	ds_read2_b32 v[50:51], v55 offset0:22 offset1:30
	ds_read2_b32 v[52:53], v55 offset0:55 offset1:63
	global_store_dwordx4 v[36:37], v[32:35], off
	v_or_b32_e32 v36, s5, v74
	v_mad_i64_i32 v[36:37], s[2:3], s4, v36, 0
	v_lshl_add_u64 v[36:37], v[36:37], 1, s[6:7]
	v_lshl_add_u64 v[36:37], v[36:37], 0, s[0:1]
	s_waitcnt lgkmcnt(6)
	v_cvt_pk_bf16_f32 v32, v38, v40
	s_waitcnt lgkmcnt(4)
	v_cvt_pk_bf16_f32 v33, v42, v44
	s_waitcnt lgkmcnt(2)
	v_cvt_pk_bf16_f32 v34, v46, v48
	s_waitcnt lgkmcnt(0)
	v_cvt_pk_bf16_f32 v35, v50, v52
	v_lshl_add_u64 v[36:37], v[36:37], 0, v[64:65]
	global_store_dwordx4 v[36:37], v[32:35], off
	v_or_b32_e32 v36, s5, v75
	v_mad_i64_i32 v[36:37], s[2:3], s4, v36, 0
	v_lshl_add_u64 v[36:37], v[36:37], 1, s[6:7]
	v_lshl_add_u64 v[36:37], v[36:37], 0, s[0:1]
	v_cvt_pk_bf16_f32 v32, v39, v41
	v_cvt_pk_bf16_f32 v33, v43, v45
	v_cvt_pk_bf16_f32 v34, v47, v49
	v_cvt_pk_bf16_f32 v35, v51, v53
	v_lshl_add_u64 v[36:37], v[36:37], 0, v[64:65]
	global_store_dwordx4 v[36:37], v[32:35], off
	s_waitcnt lgkmcnt(0)
	s_branch .LBB0_439
